# A0 tile loop: wave-uniform activity test shortened from v_cndmask+v_cmp to one s_andn2_b64 (on top of the loop-head tightening)
# speedup vs baseline: 1.0075x; 1.0075x over previous
; DI unsigned cvtpk(float lo, float hi) { f32x2 v = {lo, hi}; return __builtin_bit_cast(unsigned, __builtin_convertvector(v, bf16x2_t)); }
; template <int DQK, int NHQ, int NHKV, bool HAS_META>
; DI void attn_phase(const u16* __restrict__ Q, const u16* __restrict__ K, const u16* __restrict__ Vt, u16* __restrict__ O, const float* __restrict__ qg, const float* __restrict__ kg, char* smem, const int wv) {
;     ...
;       __builtin_amdgcn_s_setprio(0);
;       if (active) {
;         f32x2 ps2 = {0.f, 0.f};
;         unsigned w_[16];
; #pragma unroll
;         for (int i = 0; i < 8; ++i) {
;           f32x2 v;
;           v[0] = __builtin_amdgcn_exp2f(s0[2 * i]); v[1] = __builtin_amdgcn_exp2f(s0[2 * i + 1]);
;           if (j == NT - 1 && i >= 4) v = f32x2{0.f, 0.f};
;           ps2 += v;
;           w_[i] = cvtpk(v[0], v[1]);
;         }
; #pragma unroll
;         for (int i = 0; i < 8; ++i) {
;           f32x2 v;
;           v[0] = __builtin_amdgcn_exp2f(s1[2 * i]); v[1] = __builtin_amdgcn_exp2f(s1[2 * i + 1]);
;           if (j == NT - 1) v = f32x2{0.f, 0.f};
;           ps2 += v;
;           w_[8 + i] = cvtpk(v[0], v[1]);
;         }
;         l += xhalf_sum(ps2[0] + ps2[1]);
;         pb[0] = __builtin_bit_cast(bf16x8, u32x4{w_[0], w_[1], w_[2], w_[3]});
;         pb[1] = __builtin_bit_cast(bf16x8, u32x4{w_[4], w_[5], w_[6], w_[7]});
;         pb[2] = __builtin_bit_cast(bf16x8, u32x4{w_[8], w_[9], w_[10], w_[11]});
;         pb[3] = __builtin_bit_cast(bf16x8, u32x4{w_[12], w_[13], w_[14], w_[15]});
.Lmy_a0_nodef_loop:
	s_setprio 0
	s_andn2_b64 s[4:5], exec, s[30:31]
	s_andn2_b64 vcc, exec, s[30:31]
	s_cbranch_vccnz .LBB0_678
	v_exp_f32_e32 v2, v16
	v_exp_f32_e32 v3, v17
	v_exp_f32_e32 v4, v18
	v_exp_f32_e32 v5, v19
	v_exp_f32_e32 v8, v22
	v_pk_add_f32 v[6:7], v[2:3], 0 op_sel_hi:[1,0]
	v_cvt_pk_bf16_f32 v112, v2, v3
	v_pk_add_f32 v[2:3], v[4:5], v[6:7]
	v_exp_f32_e32 v6, v20
	v_exp_f32_e32 v7, v21
	v_exp_f32_e32 v9, v23
	v_cvt_pk_bf16_f32 v113, v4, v5
	v_exp_f32_e32 v4, v24
	v_exp_f32_e32 v5, v25
	v_pk_add_f32 v[2:3], v[6:7], v[2:3]
	v_cvt_pk_bf16_f32 v114, v6, v7
	v_pk_add_f32 v[2:3], v[8:9], v[2:3]
	v_exp_f32_e32 v6, v26
	v_exp_f32_e32 v7, v27
	v_pk_add_f32 v[2:3], v[4:5], v[2:3]
	v_cvt_pk_bf16_f32 v128, v4, v5
	v_exp_f32_e32 v4, v28
	v_exp_f32_e32 v5, v29
	v_cvt_pk_bf16_f32 v115, v8, v9
	v_pk_add_f32 v[2:3], v[6:7], v[2:3]
	v_exp_f32_e32 v8, v30
	v_exp_f32_e32 v9, v31
	v_pk_add_f32 v[2:3], v[4:5], v[2:3]
	v_cvt_pk_bf16_f32 v130, v4, v5
	v_exp_f32_e32 v4, v32
	v_exp_f32_e32 v5, v33
	v_cvt_pk_bf16_f32 v129, v6, v7
	v_pk_add_f32 v[2:3], v[8:9], v[2:3]
	v_exp_f32_e32 v6, v34
	v_exp_f32_e32 v7, v35
	v_pk_add_f32 v[2:3], v[4:5], v[2:3]
	v_cvt_pk_bf16_f32 v132, v4, v5
	v_exp_f32_e32 v4, v36
	v_exp_f32_e32 v5, v37
	v_cvt_pk_bf16_f32 v131, v8, v9
	v_pk_add_f32 v[2:3], v[6:7], v[2:3]
	v_exp_f32_e32 v8, v38
	v_exp_f32_e32 v9, v39
	v_pk_add_f32 v[2:3], v[4:5], v[2:3]
	v_cvt_pk_bf16_f32 v134, v4, v5
	v_exp_f32_e32 v4, v40
	v_exp_f32_e32 v5, v41
	v_cvt_pk_bf16_f32 v133, v6, v7
	v_pk_add_f32 v[2:3], v[8:9], v[2:3]
	v_exp_f32_e32 v6, v42
	v_exp_f32_e32 v7, v43
	v_pk_add_f32 v[2:3], v[4:5], v[2:3]
	v_cvt_pk_bf16_f32 v136, v4, v5
	v_exp_f32_e32 v4, v44
	v_exp_f32_e32 v5, v45
	v_cvt_pk_bf16_f32 v135, v8, v9
	v_exp_f32_e32 v8, v46
	v_exp_f32_e32 v9, v47
	v_pk_add_f32 v[2:3], v[6:7], v[2:3]
	v_cvt_pk_bf16_f32 v137, v6, v7
	v_pk_add_f32 v[2:3], v[4:5], v[2:3]
	v_cvt_pk_bf16_f32 v138, v4, v5
	v_pk_add_f32 v[2:3], v[8:9], v[2:3]
	v_cvt_pk_bf16_f32 v139, v8, v9
	v_pk_add_f32 v[2:3], v[2:3], v[2:3] op_sel:[0,1] op_sel_hi:[1,0]
	s_nop 0
	v_mov_b32_e32 v0, v2
	s_nop 1
	v_permlane32_swap_b32_e32 v2, v0
	v_add_f32_e32 v0, v2, v0
	v_add_f32_e32 v221, v221, v0
